# phase-0 table conversion loop: look-ahead loads of the next element group in flight (two buffers, counted waits) instead of one load at a time with vmcnt(0)
# speedup vs baseline: 1.0034x; 1.0034x over previous
.LBB0_33:
	v_lshl_add_u32 v4, s2, 9, v1
	s_mov_b32 s3, 0x400000
	s_lshl_b32 s6, s67, 9
	v_cmp_gt_i32_e32 vcc, s3, v4
	v_ashrrev_i32_e32 v5, 31, v4
	s_and_saveexec_b64 s[8:9], vcc
	s_cbranch_execz .LBB0_36
	s_add_u32 s10, s0, 0x2000000
	s_addc_u32 s11, s1, 0
	s_add_u32 s12, s0, 0x4000000
	s_addc_u32 s13, s1, 0
	s_ashr_i32 s7, s6, 31
	s_lshl_b32 s3, s67, 11
	s_lshl_b64 s[14:15], s[6:7], 4
	s_lshl_b32 s22, s67, 25
	s_add_u32 s16, s96, s4
	s_addc_u32 s17, s97, s5
	v_lshl_add_u64 v[8:9], v[4:5], 3, s[16:17]
	s_mov_b64 s[16:17], 0x6000000
	v_lshl_add_u64 v[8:9], v[8:9], 0, s[16:17]
	s_lshl_b64 s[16:17], s[6:7], 3
	v_lshlrev_b32_e32 v3, 2, v1
	v_lshlrev_b32_e32 v1, 16, v1
	s_add_u32 s18, s70, 8
	v_lshl_add_u32 v3, s2, 11, v3
	v_lshlrev_b64 v[6:7], 4, v[4:5]
	v_lshl_add_u32 v1, s2, 25, v1
	s_addc_u32 s19, s71, 0
	s_mov_b64 s[20:21], 0
	v_mov_b32_e32 v11, 0
	s_movk_i32 s7, 0x7c
	s_mov_b32 s23, 0x3fffff
	v_mov_b32_e32 v12, v4
	v_mov_b32_e32 v243, v4
	v_mov_b32_e32 v239, 0
	v_mov_b32_e32 v245, 0
	v_lshlrev_b32_e32 v238, 4, v243
	v_lshl_add_u64 v[240:241], s[56:57], 0, v[238:239]
	global_load_dwordx4 v[214:217], v[240:241], off
	v_lshl_add_u64 v[240:241], s[58:59], 0, v[238:239]
	global_load_dwordx4 v[218:221], v[240:241], off
	v_lshl_add_u64 v[240:241], s[70:71], 0, v[238:239]
	global_load_dwordx4 v[222:225], v[240:241], off
	global_load_dword v252, v[240:241], off
	global_load_dword v252, v[240:241], off
	global_load_dword v252, v[240:241], off
.Ltbl_loop:
	v_add_u32_e32 v242, s6, v243
	v_and_b32_e32 v242, 0x3fffff, v242
	v_lshlrev_b32_e32 v238, 4, v242
	v_lshl_add_u64 v[240:241], s[56:57], 0, v[238:239]
	global_load_dwordx4 v[226:229], v[240:241], off
	v_lshl_add_u64 v[240:241], s[58:59], 0, v[238:239]
	global_load_dwordx4 v[230:233], v[240:241], off
	v_lshl_add_u64 v[240:241], s[70:71], 0, v[238:239]
	global_load_dwordx4 v[234:237], v[240:241], off
	s_waitcnt vmcnt(6)
	v_ashrrev_i32_e32 v244, 8, v243
	v_bfe_u32 v246, v243, 5, 3
	v_lshlrev_b32_e32 v244, 7, v244
	v_and_b32_e32 v247, 31, v243
	v_lshl_or_b32 v244, v246, 21, v244
	v_lshl_or_b32 v244, v247, 2, v244
	v_mul_f32_e32 v214, 0x42800000, v214
	v_mul_f32_e32 v215, 0x42800000, v215
	v_mul_f32_e32 v216, 0x42800000, v216
	v_mul_f32_e32 v217, 0x42800000, v217
	v_lshl_add_u64 v[240:241], s[10:11], 0, v[244:245]
	v_cvt_pk_fp8_f32 v248, v214, v215
	v_cvt_pk_fp8_f32 v248, v216, v217 op_sel:[0,0,1]
	global_store_dword v[240:241], v248, off
	v_mul_f32_e32 v218, 0x41800000, v218
	v_mul_f32_e32 v219, 0x41800000, v219
	v_mul_f32_e32 v220, 0x41800000, v220
	v_mul_f32_e32 v221, 0x41800000, v221
	v_lshl_add_u64 v[240:241], s[12:13], 0, v[244:245]
	v_cvt_pk_fp8_f32 v249, v218, v219
	v_cvt_pk_fp8_f32 v249, v220, v221 op_sel:[0,0,1]
	global_store_dword v[240:241], v249, off
	v_cvt_pk_bf16_f32 v250, v222, v223
	v_cvt_pk_bf16_f32 v251, v224, v225
	global_store_dwordx2 v[8:9], v[250:251], off
	v_lshl_add_u64 v[8:9], v[8:9], 0, s[16:17]
	v_add_u32_e32 v243, s6, v243
	v_cmp_ge_i32_e32 vcc, s23, v243
	s_and_b64 exec, exec, vcc
	s_cbranch_execz .Ltbl_done
	v_add_u32_e32 v242, s6, v243
	v_and_b32_e32 v242, 0x3fffff, v242
	v_lshlrev_b32_e32 v238, 4, v242
	v_lshl_add_u64 v[240:241], s[56:57], 0, v[238:239]
	global_load_dwordx4 v[214:217], v[240:241], off
	v_lshl_add_u64 v[240:241], s[58:59], 0, v[238:239]
	global_load_dwordx4 v[218:221], v[240:241], off
	v_lshl_add_u64 v[240:241], s[70:71], 0, v[238:239]
	global_load_dwordx4 v[222:225], v[240:241], off
	s_waitcnt vmcnt(6)
	v_ashrrev_i32_e32 v244, 8, v243
	v_bfe_u32 v246, v243, 5, 3
	v_lshlrev_b32_e32 v244, 7, v244
	v_and_b32_e32 v247, 31, v243
	v_lshl_or_b32 v244, v246, 21, v244
	v_lshl_or_b32 v244, v247, 2, v244
	v_mul_f32_e32 v226, 0x42800000, v226
	v_mul_f32_e32 v227, 0x42800000, v227
	v_mul_f32_e32 v228, 0x42800000, v228
	v_mul_f32_e32 v229, 0x42800000, v229
	v_lshl_add_u64 v[240:241], s[10:11], 0, v[244:245]
	v_cvt_pk_fp8_f32 v248, v226, v227
	v_cvt_pk_fp8_f32 v248, v228, v229 op_sel:[0,0,1]
	global_store_dword v[240:241], v248, off
	v_mul_f32_e32 v230, 0x41800000, v230
	v_mul_f32_e32 v231, 0x41800000, v231
	v_mul_f32_e32 v232, 0x41800000, v232
	v_mul_f32_e32 v233, 0x41800000, v233
	v_lshl_add_u64 v[240:241], s[12:13], 0, v[244:245]
	v_cvt_pk_fp8_f32 v249, v230, v231
	v_cvt_pk_fp8_f32 v249, v232, v233 op_sel:[0,0,1]
	global_store_dword v[240:241], v249, off
	v_cvt_pk_bf16_f32 v250, v234, v235
	v_cvt_pk_bf16_f32 v251, v236, v237
	global_store_dwordx2 v[8:9], v[250:251], off
	v_lshl_add_u64 v[8:9], v[8:9], 0, s[16:17]
	v_add_u32_e32 v243, s6, v243
	v_cmp_ge_i32_e32 vcc, s23, v243
	s_and_b64 exec, exec, vcc
	s_cbranch_execnz .Ltbl_loop
.Ltbl_done:
.LBB0_36:
	s_or_b64 exec, exec, s[8:9]
	s_mov_b32 s3, 0x10000
	v_cmp_gt_i32_e32 vcc, s3, v4
	s_and_saveexec_b64 s[8:9], vcc
	s_cbranch_execz .LBB0_39
	s_ashr_i32 s7, s6, 31
	s_lshl_b64 s[10:11], s[6:7], 4
	s_add_u32 s12, s96, s4
	v_mov_b32_e32 v6, s54
	v_mov_b32_e32 v7, s55
	s_addc_u32 s13, s97, s5
	v_lshl_add_u64 v[6:7], v[4:5], 4, v[6:7]
	v_lshl_add_u64 v[8:9], v[4:5], 3, s[12:13]
	s_mov_b64 s[12:13], 0x1880000
	v_lshl_add_u64 v[6:7], v[6:7], 0, 8
	v_lshl_add_u64 v[8:9], v[8:9], 0, s[12:13]
	s_lshl_b64 s[12:13], s[6:7], 3
	s_mov_b64 s[14:15], 0
	s_mov_b32 s3, 0xffff
	v_mov_b32_e32 v1, v4
